# workgroup-class work queues (dif/fox/nsa): snapshot the 8 queue heads with one vector load when the own queue runs dry and skip drained queues
# speedup vs baseline: 1.0054x; 1.0054x over previous
; __device__ __forceinline__ unsigned xb_xcc_id() { return (unsigned)__builtin_amdgcn_s_getreg((3 << 11) | 20) & 0xFu; }
; __device__ __forceinline__ float wave_sum(float v) { v += lx<1>(v); v += lx<2>(v); v += lx<4>(v); v += lx<8>(v); v += lx<16>(v); return half_sum(v); }
; #define ARG_IN(i) ((const float*)karg64(8 * (i)))
; #define ARG_WS() ((unsigned char*)karg64(8 * 19))
; #define WG_DRAW(cls, q) LAS int* slot = (LAS int*)(lds + MISC_OFF + 64); \
;         if (threadIdx.x == 0) *slot = (int)__hip_atomic_fetch_add(XQ_HEAD(cls, q), 1u, RLX_AGENT); \
;         __syncthreads(); const int it = *slot; __syncthreads();
; template <int ATTM> __device__ __forceinline__ void attention_phase(int layer, int lane, int rep, LAS unsigned char* lds, int wave) {
;     ...
;     if ((ATTM & 2) && PK(2)) {
; #pragma unroll 1
;         for (int qq = 0; qq < 8; ++qq) { const int q = ((int)(xb_xcc_id() & 7u) + qq) & 7;
;             for (;;) { WG_DRAW(0, q); if (it >= 32) break;
;                 unsigned char* ws = ARG_WS(); int tid = threadIdx.x; asm volatile("" : "+v"(tid));
;                 const float* lamv = ARG_IN(A_LAM) + (size_t)layer * 4 * 64;
;                 const float lam_init = 0.8f - 0.6f * __builtin_amdgcn_exp2f(-0.3f * 1.4426950408889634f * (float)layer);
;                 const float sa = wave_sum(lamv[lane] * lamv[64 + lane]), sb = wave_sum(lamv[128 + lane] * lamv[192 + lane]);
;                 const float lam = __builtin_amdgcn_exp2f(1.4426950408889634f * sa) - __builtin_amdgcn_exp2f(1.4426950408889634f * sb) + lam_init;
;                 dif_coop(WSP(bf16, WS_PROJ), ws + WS_VTB, WSP(bf16, WS_O), lam, ARG_IN(A_SUBG) + (size_t)layer * 128, 1.f - lam_init, q, 31 - it, lds, tid); } } }
.LBB0_546:
	s_andn2_b64 vcc, exec, s[2:3]
	s_cbranch_vccnz .LBB0_2026
	v_readlane_b32 s6, v255, 21
	s_load_dword s4, s[72:73], 0x0
	v_mov_b32_e32 v4, v0
	v_cvt_f32_u32_e32 v1, s6
	v_mov_b32_e32 v2, 0x3f4ccccd
	s_waitcnt lgkmcnt(0)
	v_mul_f32_e32 v1, 0xbedd9914, v1
	v_exp_f32_e32 v1, v1
	v_readlane_b32 s7, v255, 22
	v_readfirstlane_b32 s4, v4
	s_mul_i32 s33, s6, 40
	v_fmamk_f32 v1, v1, 0xbf19999a, v2
	v_and_b32_e32 v2, 63, v4
	s_lshl_b64 s[2:3], s[6:7], 10
	s_lshl_b64 s[72:73], s[6:7], 9
	s_waitcnt vmcnt(0)
	v_sub_f32_e32 v182, 1.0, v1
	s_ashr_i32 s94, s4, 6
	s_mov_b32 s6, 0
	s_mov_b32 s101, 0
	v_lshlrev_b32_e32 v172, 2, v2
	s_branch .LBB0_549
.LBB0_548:
	s_cmp_lg_u32 s6, 0
	s_cbranch_scc1 .Lmy_qs_dif_inc
	v_cmp_gt_u32_e32 vcc, 8, v0
	s_and_saveexec_b64 s[14:15], vcc
	s_cbranch_execz .Lmy_qs_dif_b
	s_load_dwordx2 s[12:13], s[0:1], 0x98
	s_lshl_b32 s4, s33, 7
	s_add_i32 s4, s4, 0x20000

; __device__ __forceinline__ unsigned xb_xcc_id() { return (unsigned)__builtin_amdgcn_s_getreg((3 << 11) | 20) & 0xFu; }
; #define WG_DRAW(cls, q) LAS int* slot = (LAS int*)(lds + MISC_OFF + 64); \
;         if (threadIdx.x == 0) *slot = (int)__hip_atomic_fetch_add(XQ_HEAD(cls, q), 1u, RLX_AGENT); \
;         __syncthreads(); const int it = *slot; __syncthreads();
; template <int ATTM> __device__ __forceinline__ void attention_phase(int layer, int lane, int rep, LAS unsigned char* lds, int wave) {
;     ...
;     if ((ATTM & 2) && PK(2)) {
; #pragma unroll 1
;         for (int qq = 0; qq < 8; ++qq) { const int q = ((int)(xb_xcc_id() & 7u) + qq) & 7;
;             for (;;) { WG_DRAW(0, q); if (it >= 32) break;
	v_lshl_add_u32 v5, v0, 7, s4
	s_waitcnt lgkmcnt(0)
	global_load_dword v6, v5, s[12:13] sc1
	s_waitcnt vmcnt(0)
	v_cmp_le_u32_e32 vcc, 0x20, v6
	s_nop 1
	s_and_b32 s4, vcc_lo, 0xff
	v_mov_b32_e32 v6, s4
	v_mov_b32_e32 v5, s87
	ds_write_b32 v5, v6 offset:4
.Lmy_qs_dif_b:
	s_or_b64 exec, exec, s[14:15]
	s_waitcnt lgkmcnt(0)
	s_barrier
	v_mov_b32_e32 v5, s87
	ds_read_b32 v5, v5 offset:4
	s_waitcnt lgkmcnt(0)
	v_readfirstlane_b32 s101, v5

; #define LAS __attribute__((address_space(3)))
; __device__ __forceinline__ unsigned xb_xcc_id() { return (unsigned)__builtin_amdgcn_s_getreg((3 << 11) | 20) & 0xFu; }
; __device__ __forceinline__ float wave_sum(float v) { v += lx<1>(v); v += lx<2>(v); v += lx<4>(v); v += lx<8>(v); v += lx<16>(v); return half_sum(v); }
; #define ARG_IN(i) ((const float*)karg64(8 * (i)))
; #define ARG_WS() ((unsigned char*)karg64(8 * 19))
; #define WG_DRAW(cls, q) LAS int* slot = (LAS int*)(lds + MISC_OFF + 64); \
;         if (threadIdx.x == 0) *slot = (int)__hip_atomic_fetch_add(XQ_HEAD(cls, q), 1u, RLX_AGENT); \
;         __syncthreads(); const int it = *slot; __syncthreads();
; __device__ __forceinline__ void dif_coop(const bf16* PROJ, const unsigned char* VTB, bf16* O, float lam, const float* subg, float oscale, int bh, int c, LAS unsigned char* sbuf, int tid) {
;     const int wave = tid >> 6, lane = tid & 63, b = bh >> 2, hd = bh & 3, q = lane & 31, hh = lane >> 5, mp = wave >> 2, qt = 4 * c + (wave & 3), tq = 32 * qt + q; const size_t row = (size_t)b * SEQ + tq;
;     AlibiCausal f; f.setup(__builtin_amdgcn_exp2f(-2.f * (float)(hd + 1)) * LOG2E, hh); f.tq = tq; f.t0 = 32 * qt;
; template <int ATTM> __device__ __forceinline__ void attention_phase(int layer, int lane, int rep, LAS unsigned char* lds, int wave) {
;     ...
;         for (int qq = 0; qq < 8; ++qq) { const int q = ((int)(xb_xcc_id() & 7u) + qq) & 7;
;             for (;;) { WG_DRAW(0, q); if (it >= 32) break;
;                 unsigned char* ws = ARG_WS(); int tid = threadIdx.x; asm volatile("" : "+v"(tid));
;                 const float* lamv = ARG_IN(A_LAM) + (size_t)layer * 4 * 64;
;                 const float lam_init = 0.8f - 0.6f * __builtin_amdgcn_exp2f(-0.3f * 1.4426950408889634f * (float)layer);
;                 const float sa = wave_sum(lamv[lane] * lamv[64 + lane]), sb = wave_sum(lamv[128 + lane] * lamv[192 + lane]);
;                 const float lam = __builtin_amdgcn_exp2f(1.4426950408889634f * sa) - __builtin_amdgcn_exp2f(1.4426950408889634f * sb) + lam_init;
;                 dif_coop(WSP(bf16, WS_PROJ), ws + WS_VTB, WSP(bf16, WS_O), lam, ARG_IN(A_SUBG) + (size_t)layer * 128, 1.f - lam_init, q, 31 - it, lds, tid); } } }
.LBB0_549:
	s_getreg_b32 s4, hwreg(HW_REG_XCC_ID, 0, 4)
	s_add_i32 s4, s4, s6
	s_and_b32 s5, s4, 3
	s_not_b32 s7, s5
	s_lshl_b32 s7, s7, 1
	v_cvt_f32_i32_e32 v2, s7
	s_and_b32 s7, s4, 7
	s_bitcmp1_b32 s101, s7
	s_cbranch_scc1 .LBB0_548
	s_bfe_u32 s4, s4, 0x10002
	s_or_b32 s9, s7, s33
	v_exp_f32_e32 v2, v2
	s_lshl_b32 s8, s5, 7
	s_lshl_b32 s18, s9, 5
	s_mul_i32 s10, s4, 0x1800000
	v_mul_f32_e32 v183, 0x3fb8aa3b, v2
	v_mul_f32_e32 v174, 0x40b17218, v183
	s_lshl_b32 s5, s5, 1
	s_mul_i32 s9, s4, 28
	s_lshl_b32 s7, s4, 12
	s_add_i32 s9, s9, s5
	v_mov_b32_e32 v176, v174
	v_mov_b32_e32 v177, v174
	s_lshl_b64 s[26:27], s[18:19], 2
	s_lshl_b32 s10, s10, 1
	s_branch .LBB0_552

; __device__ __forceinline__ unsigned xb_xcc_id() { return (unsigned)__builtin_amdgcn_s_getreg((3 << 11) | 20) & 0xFu; }
; #define WG_DRAW(cls, q) LAS int* slot = (LAS int*)(lds + MISC_OFF + 64); \
;         if (threadIdx.x == 0) *slot = (int)__hip_atomic_fetch_add(XQ_HEAD(cls, q), 1u, RLX_AGENT); \
;         __syncthreads(); const int it = *slot; __syncthreads();
; template <int ATTM> __device__ __forceinline__ void attention_phase(int layer, int lane, int rep, LAS unsigned char* lds, int wave) {
;     ...
;     if ((ATTM & 1) && PK(1)) {
; #pragma unroll 1
;         for (int qq = 0; qq < 8; ++qq) { const int q = ((int)(xb_xcc_id() & 7u) + qq) & 7; const int two = q + 8 < BATCH * 7 ? 1 : 0;
;             for (;;) { WG_DRAW(1, q); if (it >= (two ? 32 : 16)) break;
.LBB0_613:
	s_add_i32 s6, s33, 8
	s_mov_b32 s7, 0
	s_mov_b32 s101, 0
	s_branch .LBB0_615
.LBB0_614:
	s_cmp_lg_u32 s7, 0
	s_cbranch_scc1 .Lmy_qs_fox_inc
	v_cmp_gt_u32_e32 vcc, 8, v0
	s_and_saveexec_b64 s[14:15], vcc
	s_cbranch_execz .Lmy_qs_fox_b
	s_load_dwordx2 s[12:13], s[0:1], 0x98
	s_lshl_b32 s4, s6, 7
	s_add_i32 s4, s4, 0x20000

; __device__ __forceinline__ unsigned xb_xcc_id() { return (unsigned)__builtin_amdgcn_s_getreg((3 << 11) | 20) & 0xFu; }
; #define WG_DRAW(cls, q) LAS int* slot = (LAS int*)(lds + MISC_OFF + 64); \
;         if (threadIdx.x == 0) *slot = (int)__hip_atomic_fetch_add(XQ_HEAD(cls, q), 1u, RLX_AGENT); \
;         __syncthreads(); const int it = *slot; __syncthreads();
; template <int ATTM> __device__ __forceinline__ void attention_phase(int layer, int lane, int rep, LAS unsigned char* lds, int wave) {
;     ...
;         for (int qq = 0; qq < 8; ++qq) { const int q = ((int)(xb_xcc_id() & 7u) + qq) & 7; const int two = q + 8 < BATCH * 7 ? 1 : 0;
;             for (;;) { WG_DRAW(1, q); if (it >= (two ? 32 : 16)) break;
	v_lshl_add_u32 v5, v0, 7, s4
	v_mov_b32_e32 v7, 32
	v_cmp_gt_u32_e32 vcc, 6, v0
	s_nop 1
	v_cndmask_b32_e32 v7, 16, v7, vcc
	s_waitcnt lgkmcnt(0)
	global_load_dword v6, v5, s[12:13] sc1
	s_waitcnt vmcnt(0)
	v_cmp_le_u32_e32 vcc, v7, v6
	s_nop 1
	s_and_b32 s4, vcc_lo, 0xff
	v_mov_b32_e32 v6, s4
	v_mov_b32_e32 v5, s87
	ds_write_b32 v5, v6 offset:4

; __device__ __forceinline__ unsigned xb_xcc_id() { return (unsigned)__builtin_amdgcn_s_getreg((3 << 11) | 20) & 0xFu; }
; #define ARG_WS() ((unsigned char*)karg64(8 * 19))
; #define WG_DRAW(cls, q) LAS int* slot = (LAS int*)(lds + MISC_OFF + 64); \
;         if (threadIdx.x == 0) *slot = (int)__hip_atomic_fetch_add(XQ_HEAD(cls, q), 1u, RLX_AGENT); \
;         __syncthreads(); const int it = *slot; __syncthreads();
; template <int ATTM> __device__ __forceinline__ void attention_phase(int layer, int lane, int rep, LAS unsigned char* lds, int wave) {
;     ...
;         for (int qq = 0; qq < 8; ++qq) { const int q = ((int)(xb_xcc_id() & 7u) + qq) & 7; const int two = q + 8 < BATCH * 7 ? 1 : 0;
;             for (;;) { WG_DRAW(1, q); if (it >= (two ? 32 : 16)) break;
;                 unsigned char* ws = ARG_WS(); int tid = threadIdx.x; asm volatile("" : "+v"(tid));
;                 const int bh = two ? ((it & 1) ? q + 8 : q) : q, c = 15 - (two ? (it >> 1) : it);
;                 fox_coop(WSP(bf16, WS_PROJ), WSP(float, WS_CUM), ws + WS_VTB, WSP(bf16, WS_O), bh, c, lds, tid); } } }
.LBB0_615:
	s_getreg_b32 s2, hwreg(HW_REG_XCC_ID, 0, 4)
	s_add_i32 s2, s2, s7
	s_and_b32 s8, s2, 7
	s_bitcmp1_b32 s101, s8
	s_cbranch_scc1 .LBB0_614
	s_or_b32 s2, s8, 8
	s_cmp_lt_u32 s2, 14
	s_cselect_b64 s[2:3], -1, 0
	s_and_b64 s[4:5], s[2:3], exec
	s_cselect_b32 s9, 32, 16
	s_or_b32 s4, s8, s6
	v_cndmask_b32_e64 v1, 0, 1, s[2:3]
	s_lshl_b32 s18, s4, 5
	v_readfirstlane_b32 s10, v1
	s_lshl_b64 s[14:15], s[18:19], 2
	s_branch .LBB0_619

; #define LAS __attribute__((address_space(3)))
; __device__ __forceinline__ unsigned xb_xcc_id() { return (unsigned)__builtin_amdgcn_s_getreg((3 << 11) | 20) & 0xFu; }
; __device__ __forceinline__ int fresh_lane() { int l = (int)__builtin_amdgcn_mbcnt_hi(~0u, __builtin_amdgcn_mbcnt_lo(~0u, 0u)); asm volatile("" : "+v"(l)); return l; }
; #define ARG_WS() ((unsigned char*)karg64(8 * 19))
; #define WG_DRAW(cls, q) LAS int* slot = (LAS int*)(lds + MISC_OFF + 64); \
;         if (threadIdx.x == 0) *slot = (int)__hip_atomic_fetch_add(XQ_HEAD(cls, q), 1u, RLX_AGENT); \
;         __syncthreads(); const int it = *slot; __syncthreads();
; __device__ __forceinline__ void nsa_quad_item(const bf16* PROJ, const bf16* KC, const unsigned char* VCB, const unsigned char* VTB, const unsigned long long* SEL, bf16* O, LAS unsigned char* lds, int bg, int jp, int wave) {
;     const int lane = fresh_lane();
;     const int b = bg >> 1, g = bg & 1, wi = wave & 3, qd = wave >> 2, hd = 4 * g + wi, qt = 2 * jp + qd, qto = 2 * jp + (qd ^ 1), q = lane & 31, hh = lane >> 5, t0 = qt * 32, tq = t0 + q, tmax = t0 + 31;
;     LAS unsigned char* ring = lds + qd * 65536;
; template <int ATTM> __device__ __forceinline__ void attention_phase(int layer, int lane, int rep, LAS unsigned char* lds, int wave) {
;     ...
;     if ((ATTM & 4) && PK(4)) {
; #pragma unroll 1
;         for (int qq = 0; qq < 8; ++qq) { const int q = ((int)(xb_xcc_id() & 7u) + qq) & 7;
;             for (;;) { WG_DRAW(2, q); if (it >= 32) break; unsigned char* ws = ARG_WS();
;                 nsa_quad_item(WSP(bf16, WS_PROJ), WSP(bf16, WS_KC), ws + WS_VCB, ws + WS_VTB, WSP(unsigned long long, WS_SEL), WSP(bf16, WS_O), lds, q >> 1, 2 * (31 - it) + (q & 1), wave); } } }
.LBB0_668:
	v_writelane_b32 v255, s33, 25
	s_add_i32 s2, s33, 16
	v_writelane_b32 v255, s2, 26
	s_ashr_i32 s48, s94, 2
	s_and_b32 s3, s94, 3
	v_writelane_b32 v255, s94, 27
	s_xor_b32 s49, s48, 1
	s_lshl_b32 s2, s48, 16
	s_add_i32 s94, s2, 0
	v_writelane_b32 v255, s3, 28
	s_lshl_b32 s55, s3, 10
	s_add_i32 s2, s49, 0x7d
	s_and_b32 s51, s48, 1
	s_add_i32 s56, s94, s55
	v_writelane_b32 v255, s2, 29
	s_add_i32 s2, s48, 0x7d
	s_xor_b32 s52, s51, 1
	s_lshl_b32 s53, s3, 3
	s_mul_i32 s54, s3, 0x18000
	v_writelane_b32 v255, s2, 30
	s_mov_b32 s59, 0
	s_mov_b32 s101, 0
	s_mov_b64 s[42:43], 0
	s_add_i32 s60, s56, 0x5000
	s_add_i32 s61, s56, 0x7000
	s_add_i32 s62, s56, 0x9000
	s_add_i32 s63, s56, 0xb000
	s_branch .LBB0_670
.LBB0_669:
	s_cmp_lg_u32 s59, 0
	s_cbranch_scc1 .Lmy_qs_nsa_inc
	v_cmp_gt_u32_e32 vcc, 8, v0
	s_and_saveexec_b64 s[14:15], vcc
	s_cbranch_execz .Lmy_qs_nsa_b
	s_load_dwordx2 s[12:13], s[0:1], 0x98
	v_readlane_b32 s4, v255, 26
	s_lshl_b32 s4, s4, 7
	s_add_i32 s4, s4, 0x20000

; __device__ __forceinline__ unsigned xb_xcc_id() { return (unsigned)__builtin_amdgcn_s_getreg((3 << 11) | 20) & 0xFu; }
; #define ARG_WS() ((unsigned char*)karg64(8 * 19))
; #define WG_DRAW(cls, q) LAS int* slot = (LAS int*)(lds + MISC_OFF + 64); \
;         if (threadIdx.x == 0) *slot = (int)__hip_atomic_fetch_add(XQ_HEAD(cls, q), 1u, RLX_AGENT); \
;         __syncthreads(); const int it = *slot; __syncthreads();
; template <int ATTM> __device__ __forceinline__ void attention_phase(int layer, int lane, int rep, LAS unsigned char* lds, int wave) {
;     ...
;         for (int qq = 0; qq < 8; ++qq) { const int q = ((int)(xb_xcc_id() & 7u) + qq) & 7;
;             for (;;) { WG_DRAW(2, q); if (it >= 32) break; unsigned char* ws = ARG_WS();
	v_lshl_add_u32 v5, v0, 7, s4
	s_waitcnt lgkmcnt(0)
	global_load_dword v6, v5, s[12:13] sc1
	s_waitcnt vmcnt(0)
	v_cmp_le_u32_e32 vcc, 0x20, v6
	s_nop 1
	s_and_b32 s4, vcc_lo, 0xff
	v_mov_b32_e32 v6, s4
	v_mov_b32_e32 v5, s87
	ds_write_b32 v5, v6 offset:4

; #define LAS __attribute__((address_space(3)))
; __device__ __forceinline__ unsigned xb_xcc_id() { return (unsigned)__builtin_amdgcn_s_getreg((3 << 11) | 20) & 0xFu; }
; __device__ __forceinline__ int fresh_lane() { int l = (int)__builtin_amdgcn_mbcnt_hi(~0u, __builtin_amdgcn_mbcnt_lo(~0u, 0u)); asm volatile("" : "+v"(l)); return l; }
; #define ARG_WS() ((unsigned char*)karg64(8 * 19))
; #define WG_DRAW(cls, q) LAS int* slot = (LAS int*)(lds + MISC_OFF + 64); \
;         if (threadIdx.x == 0) *slot = (int)__hip_atomic_fetch_add(XQ_HEAD(cls, q), 1u, RLX_AGENT); \
;         __syncthreads(); const int it = *slot; __syncthreads();
; __device__ __forceinline__ void nsa_quad_item(const bf16* PROJ, const bf16* KC, const unsigned char* VCB, const unsigned char* VTB, const unsigned long long* SEL, bf16* O, LAS unsigned char* lds, int bg, int jp, int wave) {
;     const int lane = fresh_lane();
;     const int b = bg >> 1, g = bg & 1, wi = wave & 3, qd = wave >> 2, hd = 4 * g + wi, qt = 2 * jp + qd, qto = 2 * jp + (qd ^ 1), q = lane & 31, hh = lane >> 5, t0 = qt * 32, tq = t0 + q, tmax = t0 + 31;
;     LAS unsigned char* ring = lds + qd * 65536;
;     ...
;     const float slope2 = __builtin_amdgcn_exp2f(-(float)(hd + 1)) * LOG2E;
; template <int ATTM> __device__ __forceinline__ void attention_phase(int layer, int lane, int rep, LAS unsigned char* lds, int wave) {
;     ...
;         for (int qq = 0; qq < 8; ++qq) { const int q = ((int)(xb_xcc_id() & 7u) + qq) & 7;
;             for (;;) { WG_DRAW(2, q); if (it >= 32) break; unsigned char* ws = ARG_WS();
;                 nsa_quad_item(WSP(bf16, WS_PROJ), WSP(bf16, WS_KC), ws + WS_VCB, ws + WS_VTB, WSP(unsigned long long, WS_SEL), WSP(bf16, WS_O), lds, q >> 1, 2 * (31 - it) + (q & 1), wave); } } }
.LBB0_670:
	s_getreg_b32 s2, hwreg(HW_REG_XCC_ID, 0, 4)
	s_and_b32 s3, s2, 15
	s_add_i32 s3, s3, s59
	s_and_b32 s4, s3, 7
	s_bitcmp1_b32 s101, s4
	s_cbranch_scc1 .LBB0_669
	v_readlane_b32 s5, v255, 26
	s_or_b32 s5, s4, s5
	s_bfe_u32 s4, s4, 0x10001
	s_lshl_b32 s6, s4, 2
	v_readlane_b32 s7, v255, 28
	s_or_b32 s6, s6, s7
	s_add_i32 s7, s6, 1
	v_cvt_f32_ubyte0_e32 v1, s7
	s_bfe_u32 s7, s3, 0x10002
	s_lshl_b32 s18, s5, 5
	s_bfe_u32 s5, s3, 0x20001
	s_lshl_b32 s3, s3, 1
	s_lshl_b32 s65, s7, 12
	s_mul_i32 s68, s7, 0x3000000
	s_mul_i32 s7, s7, 28
	s_and_b32 s64, s3, 2
	s_or_b32 s3, s7, s4
	s_lshl_b32 s66, s6, 6
	s_lshl_b32 s67, s5, 15
	s_lshl_b32 s69, s4, 6
	s_lshl_b32 s72, s3, 19
	v_exp_f32_e64 v1, -v1
	s_bitcmp1_b32 s2, 0
	s_cselect_b64 s[2:3], -1, 0
	s_xor_b64 s[2:3], s[42:43], s[2:3]
	v_cndmask_b32_e64 v2, 0, 1, s[2:3]
	v_mul_f32_e32 v1, 0x3fb8aa3b, v1
	v_readfirstlane_b32 s2, v2
	v_mul_f32_e32 v162, 0x41800000, v1
	s_lshl_b32 s2, s2, 1
	v_readlane_b32 s3, v255, 29
	v_mul_f32_e32 v148, 0x40b17218, v1
	v_mul_f32_e32 v150, 0x40b17218, v162
	s_add_i32 s74, s3, s2
	v_readlane_b32 s3, v255, 30
	s_mul_i32 s73, s6, 3
	v_mov_b32_e32 v152, v148
	v_mov_b32_e32 v153, v148
	v_mov_b32_e32 v154, v150
	v_mov_b32_e32 v155, v150
	s_add_i32 s75, s3, s2
	s_lshl_b64 s[2:3], s[18:19], 2
	s_branch .LBB0_674

; __device__ __forceinline__ unsigned xb_xcc_id() { return (unsigned)__builtin_amdgcn_s_getreg((3 << 11) | 20) & 0xFu; }
; #define ARG_WS() ((unsigned char*)karg64(8 * 19))
; #define WV_DRAW(cls, q, n) int it = 0; if (__builtin_amdgcn_mbcnt_hi(~0u, __builtin_amdgcn_mbcnt_lo(~0u, 0u)) == 0u) it = (int)__hip_atomic_fetch_add(XQ_HEAD(cls, q), (unsigned)(n), RLX_AGENT); it = __builtin_amdgcn_readfirstlane(it);
; template <int ATTM> __device__ __forceinline__ void attention_phase(int layer, int lane, int rep, LAS unsigned char* lds, int wave) {
;     ...
;     if ((ATTM & 8) && PK(8)) {
; #pragma unroll 1
;         for (int qq = 0; qq < 8; ++qq) { const int q = ((int)(xb_xcc_id() & 7u) + qq) & 7;
;             for (;;) { WV_DRAW(3, q, 1); if (it >= 96) break; unsigned char* ws = ARG_WS();
;                 const int chunk = 3 * q + it / 32, idx = (chunk & 3) * 32 + (it & 31);
;                 dil_item_mfma(WSP(bf16, WS_PROJ), ws + WS_VTB, WSP(bf16, WS_O), lds + wave * 16384, chunk >> 2, idx & 15, idx >> 4, lane); } } }
.LBB0_749:
	v_readlane_b32 s2, v255, 27
	s_lshl_b32 s2, s2, 14
	v_readlane_b32 s64, v255, 25
	s_add_i32 s46, s2, 0
	v_readlane_b32 s72, v255, 16
	v_readlane_b32 s78, v255, 18
	s_add_i32 s6, s64, 24
	s_mov_b32 s7, 0
	s_mov_b32 s101, 0
	v_cmp_eq_u32_e64 s[38:39], 0, v239
	s_add_i32 s8, s46, 0x800
	s_add_i32 s9, s46, 0x2400
	s_add_i32 s10, s46, 0x2800
	s_add_i32 s11, s46, 0x2c00
	s_add_i32 s42, s46, 0x1400
	s_add_i32 s43, s46, 0x3400
	s_add_i32 s44, s46, 0x3800
	s_add_i32 s45, s46, 0x3c00
	v_readlane_b32 s66, v254, 0
	v_readlane_b32 s67, v254, 1
	v_readlane_b32 s68, v254, 2
	v_readlane_b32 s73, v255, 17
	v_readlane_b32 s79, v255, 19
	s_branch .LBB0_751

; __device__ __forceinline__ unsigned xb_xcc_id() { return (unsigned)__builtin_amdgcn_s_getreg((3 << 11) | 20) & 0xFu; }
; __device__ __forceinline__ int fresh_lane() { int l = (int)__builtin_amdgcn_mbcnt_hi(~0u, __builtin_amdgcn_mbcnt_lo(~0u, 0u)); asm volatile("" : "+v"(l)); return l; }
; #define ARG_IN(i) ((const float*)karg64(8 * (i)))
; #define ARG_WS() ((unsigned char*)karg64(8 * 19))
; #define WV_DRAW(cls, q, n) int it = 0; if (__builtin_amdgcn_mbcnt_hi(~0u, __builtin_amdgcn_mbcnt_lo(~0u, 0u)) == 0u) it = (int)__hip_atomic_fetch_add(XQ_HEAD(cls, q), (unsigned)(n), RLX_AGENT); it = __builtin_amdgcn_readfirstlane(it);
; template <int ATTM> __device__ __forceinline__ void attention_phase(int layer, int lane, int rep, LAS unsigned char* lds, int wave) {
;     ...
;     if (!(ATTM & 32) && PK(16) && layer + 1 < DEPTH) {
; #pragma unroll 1
;         for (int qq = 0; qq < 8; ++qq) { const int q = ((int)(xb_xcc_id() & 7u) + qq) & 7;
;             for (;;) { WV_DRAW(4, q, 4); if (it >= I_LAYER / 8) break; unsigned char* ws = ARG_WS();
; #pragma unroll 1
;                 for (int k = it; k < it + 4 && k < I_LAYER / 8; ++k) conv_item(ARG_IN(A_WIN), ARG_IN(A_WOUT), ARG_IN(A_WGATE), ARG_IN(A_WUP), ARG_IN(A_WDOWN), ws, layer + 1, q * (I_LAYER / 8) + k, lds + wave * 16384, fresh_lane()); } } }
.LBB0_876:
	v_readlane_b32 s2, v255, 21
	s_cmp_eq_u32 s2, 3
	v_readlane_b32 s3, v255, 22
	s_cbranch_scc1 .LBB0_1429
	s_add_i32 s18, s2, 1
	s_mul_hi_u32 s26, s18, 0x6200000
	s_mul_i32 s27, s18, 0x6200000
	s_add_i32 s5, s64, 32
	s_lshl_b64 s[42:43], s[18:19], 24
	s_mul_hi_u32 s36, s18, 0x2c00000
	s_mul_i32 s37, s18, 0x2c00000
	s_mul_hi_u32 s47, s18, 0x2e3e000
	s_mul_i32 s48, s18, 0x2e3e000
	s_mov_b32 s49, 0
	s_mov_b32 s101, 0
	s_mov_b32 s50, 0
	s_branch .LBB0_879

; __device__ __forceinline__ unsigned xb_xcc_id() { return (unsigned)__builtin_amdgcn_s_getreg((3 << 11) | 20) & 0xFu; }
; __device__ __forceinline__ int fresh_lane() { int l = (int)__builtin_amdgcn_mbcnt_hi(~0u, __builtin_amdgcn_mbcnt_lo(~0u, 0u)); asm volatile("" : "+v"(l)); return l; }
; #define ARG_IN(i) ((const float*)karg64(8 * (i)))
; #define ARG_WS() ((unsigned char*)karg64(8 * 19))
; template <int ATTM> __device__ __forceinline__ void attention_phase(int layer, int lane, int rep, LAS unsigned char* lds, int wave) {
;     ...
;     if (!(ATTM & 32) && PK(16) && layer == 0) {
;         constexpr int I_REST = I_GU + I_D; static_assert(I_REST % 8 == 0, "");
; #pragma unroll 1
;         for (int qq = 0; qq < 8; ++qq) { const int q = ((int)(xb_xcc_id() & 7u) + qq) & 7;
;             for (;;) { int it = 0; if (__builtin_amdgcn_mbcnt_hi(~0u, __builtin_amdgcn_mbcnt_lo(~0u, 0u)) == 0u) it = (int)__hip_atomic_fetch_add((gu32*)(ARG_WS() + WS_CTL) + CW_XQ + (((DEPTH * 5 + 4) * 8 + q) * 2 + rep) * 16, 4u, RLX_AGENT);
;                 it = __builtin_amdgcn_readfirstlane(it); if (it >= I_REST / 8) break; unsigned char* ws = ARG_WS();
; #pragma unroll 1
;                 for (int k = it; k < it + 4 && k < I_REST / 8; ++k) conv_item(ARG_IN(A_WIN), ARG_IN(A_WOUT), ARG_IN(A_WGATE), ARG_IN(A_WUP), ARG_IN(A_WDOWN), ws, 0, I_IN + I_OUT + q * (I_REST / 8) + k, lds + wave * 16384, fresh_lane()); } } }
.LBB0_1442:
	s_mov_b32 s5, 0
	s_mov_b32 s101, 0
	s_mov_b32 s26, 0
	s_branch .LBB0_1444

; #define LAS __attribute__((address_space(3)))
; template <int PHM, int ATTM> __global__ void __launch_bounds__(NWAVES * 64, 2) fwd_kernel(Args args) {
;     extern __shared__ __attribute__((aligned(16))) unsigned char lds_raw[];
;     LAS unsigned char* lds = (LAS unsigned char*)lds_raw;
;     for (int u = threadIdx.x; u < (LDS_BYTES - LDSCTL_OFF) / 4; u += NWAVES * 64) ((LAS unsigned*)(lds + LDSCTL_OFF))[u] = 0u;
	.amdhsa_kernel _Z10fwd_kernelILi65535ELi15EEv4Args
		.amdhsa_group_segment_fixed_size 0
		.amdhsa_private_segment_fixed_size 0
		.amdhsa_kernarg_size 424
		.amdhsa_user_sgpr_count 2
		.amdhsa_user_sgpr_dispatch_ptr 0
		.amdhsa_user_sgpr_queue_ptr 0
		.amdhsa_user_sgpr_kernarg_segment_ptr 1
		.amdhsa_user_sgpr_dispatch_id 0
		.amdhsa_user_sgpr_kernarg_preload_length 0
		.amdhsa_user_sgpr_kernarg_preload_offset 0
		.amdhsa_user_sgpr_private_segment_size 0
		.amdhsa_uses_dynamic_stack 0
		.amdhsa_enable_private_segment 0
		.amdhsa_system_sgpr_workgroup_id_x 1
		.amdhsa_system_sgpr_workgroup_id_y 0
		.amdhsa_system_sgpr_workgroup_id_z 0
		.amdhsa_system_sgpr_workgroup_info 0
		.amdhsa_system_vgpr_workitem_id 0
		.amdhsa_next_free_vgpr 256
		.amdhsa_next_free_sgpr 102
		.amdhsa_accum_offset 256
		.amdhsa_reserve_vcc 1
		.amdhsa_float_round_mode_32 0
		.amdhsa_float_round_mode_16_64 0
		.amdhsa_float_denorm_mode_32 3
		.amdhsa_float_denorm_mode_16_64 3
		.amdhsa_dx10_clamp 1
		.amdhsa_ieee_mode 1
		.amdhsa_fp16_overflow 0
		.amdhsa_tg_split 0
		.amdhsa_exception_fp_ieee_invalid_op 0
		.amdhsa_exception_fp_denorm_src 0
		.amdhsa_exception_fp_ieee_div_zero 0
		.amdhsa_exception_fp_ieee_overflow 0
		.amdhsa_exception_fp_ieee_underflow 0
		.amdhsa_exception_fp_ieee_inexact 0
		.amdhsa_exception_int_div_zero 0
	.end_amdhsa_kernel

; #define CAS __attribute__((address_space(4)))
; __device__ __forceinline__ unsigned long long karg64(int off) { return *(volatile CAS unsigned long long*)((CAS char*)__builtin_amdgcn_kernarg_segment_ptr() + off); }
; __device__ __forceinline__ int karg32(int off) { return *(volatile CAS int*)((CAS char*)__builtin_amdgcn_kernarg_segment_ptr() + off); }
amdhsa.kernels:
  - .agpr_count:     0
    .args:
      - .offset:         0
        .size:           168
        .value_kind:     by_value
      - .offset:         168
        .size:           4
        .value_kind:     hidden_block_count_x
      - .offset:         172
        .size:           4
        .value_kind:     hidden_block_count_y
      - .offset:         176
        .size:           4
        .value_kind:     hidden_block_count_z
      - .offset:         180
        .size:           2
        .value_kind:     hidden_group_size_x
      - .offset:         182
        .size:           2
        .value_kind:     hidden_group_size_y
      - .offset:         184
        .size:           2
        .value_kind:     hidden_group_size_z
      - .offset:         186
        .size:           2
        .value_kind:     hidden_remainder_x
      - .offset:         188
        .size:           2
        .value_kind:     hidden_remainder_y
      - .offset:         190
        .size:           2
        .value_kind:     hidden_remainder_z
      - .offset:         208
        .size:           8
        .value_kind:     hidden_global_offset_x
      - .offset:         216
        .size:           8
        .value_kind:     hidden_global_offset_y
      - .offset:         224
        .size:           8
        .value_kind:     hidden_global_offset_z
      - .offset:         232
        .size:           2
        .value_kind:     hidden_grid_dims
      - .offset:         288
        .size:           4
        .value_kind:     hidden_dynamic_lds_size
    .group_segment_fixed_size: 0
    .kernarg_segment_align: 8
    .kernarg_segment_size: 424
    .language:       OpenCL C
    .language_version:
      - 2
      - 0
    .max_flat_workgroup_size: 512
    .name:           _Z10fwd_kernelILi65535ELi15EEv4Args
    .private_segment_fixed_size: 0
    .sgpr_count:     108
    .sgpr_spill_count: 97
    .symbol:         _Z10fwd_kernelILi65535ELi15EEv4Args.kd
    .uniform_work_group_size: 1
    .uses_dynamic_stack: false
    .vgpr_count:     256
    .vgpr_spill_count: 0
    .wavefront_size: 64
